# v31 + nt on the residual-stream reads of the two mid-layer norm passes
# speedup vs baseline: 1.0017x; 1.0017x over previous
; __device__ __forceinline__ float bflo(unsigned w) { return __uint_as_float(w << 16); }
; __device__ __forceinline__ float bfhi(unsigned w) { return __uint_as_float(w & 0xffff0000u); }
; __device__ __forceinline__ unsigned pkbf(float lo, float hi) { return pg8::cvt_pk_bf16(lo, hi); }
; __device__ __forceinline__ void norm_row(const float* src, const bf16_t* add, const float* gain, bf16_t* ob, float* of, int lane) {
;     f32x4 v[4]; float s = 0.f;
; #pragma unroll
;     for (int j = 0; j < 4; ++j) { v[j] = *((const f32x4*)src + lane + 64 * j);
;         if (add) { const u32x2 d = *((const u32x2*)add + lane + 64 * j); v[j][0] += bflo(d.x); v[j][1] += bfhi(d.x); v[j][2] += bflo(d.y); v[j][3] += bfhi(d.y); }
;         s += (v[j][0] * v[j][0] + v[j][1] * v[j][1]) + (v[j][2] * v[j][2] + v[j][3] * v[j][3]); }
;     const float rstd = 1.0f / sqrtf(wave_sum(s) * (1.f / DM) + NORM_EPS);
; #pragma unroll
;     for (int j = 0; j < 4; ++j) { const f32x4 g = *((const f32x4*)gain + lane + 64 * j); const f32x4 o = v[j] * rstd * g;
;         if (ob) { u32x2 w; w.x = pkbf(o[0], o[1]); w.y = pkbf(o[2], o[3]); *((u32x2*)ob + lane + 64 * j) = w; }
;         else *((f32x4*)of + lane + 64 * j) = o; }
; }
.LBB0_284:
	s_add_i32 s12, s6, 0xffff8000
	v_add_co_u32_e64 v16, s[0:1], s8, v2
	v_add_co_u32_e32 v14, vcc, s3, v2
	s_nop 0
	v_addc_co_u32_e64 v17, s[0:1], -1, v3, s[0:1]
	s_cmp_lt_i32 s6, 0x8000
	v_addc_co_u32_e32 v15, vcc, -1, v3, vcc
	s_cselect_b32 s1, s7, 0
	s_cselect_b32 s0, s6, s12
	global_load_dwordx2 v[34:35], v[14:15], off nt
	global_load_dwordx2 v[36:37], v[16:17], off offset:-3584 nt
	s_cselect_b32 s12, s17, s19
	s_cselect_b32 s13, s16, s18
	s_lshl_b64 s[0:1], s[0:1], 12
	global_load_dwordx2 v[38:39], v[16:17], off offset:-3072 nt
	global_load_dwordx2 v[40:41], v[16:17], off offset:-2560 nt
	s_add_u32 s0, s13, s0
	s_addc_u32 s1, s12, s1
	global_load_dwordx4 v[14:17], v10, s[0:1] nt
	global_load_dwordx4 v[18:21], v10, s[0:1] offset:1024 nt
	global_load_dwordx4 v[22:25], v10, s[0:1] offset:2048 nt
	global_load_dwordx4 v[26:29], v10, s[0:1] offset:3072 nt
	global_load_dwordx4 v[30:33], v[0:1], off
	s_add_u32 s6, s6, s88
	s_addc_u32 s7, s7, s89
	s_cmp_gt_i32 s6, 0xbfff
	s_waitcnt vmcnt(8)
	v_lshlrev_b32_e32 v42, 16, v34
	v_and_b32_e32 v43, 0xffff0000, v34
	v_lshlrev_b32_e32 v34, 16, v35
	v_and_b32_e32 v35, 0xffff0000, v35
	s_waitcnt vmcnt(7)
	v_lshlrev_b32_e32 v44, 16, v36
	v_and_b32_e32 v45, 0xffff0000, v36
	v_lshlrev_b32_e32 v36, 16, v37
	v_and_b32_e32 v37, 0xffff0000, v37
	s_waitcnt vmcnt(5)
	v_lshlrev_b32_e32 v48, 16, v40
	v_and_b32_e32 v49, 0xffff0000, v40
	v_lshlrev_b32_e32 v40, 16, v41
	v_and_b32_e32 v41, 0xffff0000, v41
	s_waitcnt vmcnt(4)
	v_pk_add_f32 v[14:15], v[14:15], v[42:43]
	v_pk_add_f32 v[16:17], v[16:17], v[34:35]
	s_waitcnt vmcnt(3)
	v_pk_add_f32 v[18:19], v[18:19], v[44:45]
	v_pk_add_f32 v[20:21], v[20:21], v[36:37]
	v_lshlrev_b32_e32 v46, 16, v38
	v_and_b32_e32 v47, 0xffff0000, v38
	v_lshlrev_b32_e32 v38, 16, v39
	v_and_b32_e32 v39, 0xffff0000, v39
	s_waitcnt vmcnt(1)
	v_pk_add_f32 v[28:29], v[28:29], v[40:41]
	v_mov_b32_e32 v36, v15
	v_mov_b32_e32 v37, v17
	v_mov_b32_e32 v40, v19
	v_mov_b32_e32 v41, v21
	v_pk_add_f32 v[22:23], v[22:23], v[46:47]
	v_pk_add_f32 v[24:25], v[24:25], v[38:39]
	v_mov_b32_e32 v34, v14
	v_mov_b32_e32 v35, v16
	v_mov_b32_e32 v38, v18
	v_mov_b32_e32 v39, v20
	v_pk_mul_f32 v[36:37], v[36:37], v[36:37]
	v_pk_mul_f32 v[40:41], v[40:41], v[40:41]
	v_pk_add_f32 v[26:27], v[26:27], v[48:49]
	v_mul_f32_e32 v42, v23, v23
	v_mul_f32_e32 v44, v25, v25
	v_pk_fma_f32 v[34:35], v[34:35], v[34:35], v[36:37]
	v_pk_fma_f32 v[36:37], v[38:39], v[38:39], v[40:41]
	v_pk_mul_f32 v[46:47], v[26:27], v[26:27]
	v_pk_mul_f32 v[48:49], v[28:29], v[28:29]
	v_pk_fma_f32 v[42:43], v[22:23], v[22:23], v[42:43] op_sel_hi:[1,1,0]
	v_pk_fma_f32 v[44:45], v[24:25], v[24:25], v[44:45] op_sel_hi:[1,1,0]
	v_pk_add_f32 v[34:35], v[34:35], v[34:35] op_sel:[0,1] op_sel_hi:[1,0]
	v_pk_add_f32 v[36:37], v[36:37], v[36:37] op_sel:[0,1] op_sel_hi:[1,0]
	v_mov_b32_e32 v43, v48
	v_mov_b32_e32 v45, v49
	v_mov_b32_e32 v35, v46
	v_mov_b32_e32 v37, v47
	v_pk_add_f32 v[38:39], v[42:43], v[44:45]
	v_pk_add_f32 v[34:35], v[34:35], v[36:37]
	s_nop 0
	v_pk_add_f32 v[34:35], v[34:35], v[38:39]
	s_nop 0
	v_add_f32_e32 v13, v34, v35
	ds_bpermute_b32 v34, v4, v13
	s_waitcnt lgkmcnt(0)
	v_add_f32_e32 v13, v13, v34
	ds_bpermute_b32 v34, v5, v13
	s_waitcnt lgkmcnt(0)
	v_add_f32_e32 v13, v13, v34
	ds_bpermute_b32 v34, v6, v13
	s_waitcnt lgkmcnt(0)
	v_add_f32_e32 v13, v13, v34
	ds_bpermute_b32 v34, v7, v13
	s_waitcnt lgkmcnt(0)
	v_add_f32_e32 v13, v13, v34
	ds_bpermute_b32 v34, v8, v13
	s_waitcnt lgkmcnt(0)
	v_add_f32_e32 v13, v13, v34
	ds_bpermute_b32 v34, v9, v13
	s_waitcnt lgkmcnt(0)
	v_add_f32_e32 v13, v13, v34
	v_fmamk_f32 v13, v13, 0x3a800000, v11
	v_mul_f32_e32 v34, 0x4f800000, v13
	v_cmp_gt_f32_e32 vcc, s9, v13
	s_nop 1
	v_cndmask_b32_e32 v13, v13, v34, vcc
	v_sqrt_f32_e32 v34, v13
	s_nop 0
	v_add_u32_e32 v35, -1, v34
	v_add_u32_e32 v36, 1, v34
	v_fma_f32 v37, -v35, v34, v13
	v_fma_f32 v38, -v36, v34, v13
	v_cmp_ge_f32_e64 s[0:1], 0, v37
	s_nop 1
	v_cndmask_b32_e64 v34, v34, v35, s[0:1]
	v_cmp_lt_f32_e64 s[0:1], 0, v38
	s_nop 1
	v_cndmask_b32_e64 v34, v34, v36, s[0:1]
	v_mul_f32_e32 v35, 0x37800000, v34
	v_cndmask_b32_e32 v34, v34, v35, vcc
	v_cmp_class_f32_e32 vcc, v13, v12
	s_nop 1
	v_cndmask_b32_e32 v13, v34, v13, vcc
	v_div_scale_f32 v34, s[0:1], v13, v13, 1.0
	v_rcp_f32_e32 v36, v34
	v_div_scale_f32 v35, vcc, 1.0, v13, 1.0
	v_fma_f32 v37, -v34, v36, 1.0
	v_fmac_f32_e32 v36, v37, v36
	v_mul_f32_e32 v37, v35, v36
	v_fma_f32 v38, -v34, v37, v35
	v_fmac_f32_e32 v37, v38, v36
	v_fma_f32 v34, -v34, v37, v35
	v_div_fmas_f32 v34, v34, v36, v37
	v_div_fixup_f32 v34, v34, v13, 1.0
	v_pk_mul_f32 v[14:15], v[14:15], v[34:35] op_sel_hi:[1,0]
	v_pk_mul_f32 v[16:17], v[16:17], v[34:35] op_sel_hi:[1,0]
	s_waitcnt vmcnt(0)
	v_pk_mul_f32 v[14:15], v[30:31], v[14:15]
	v_pk_mul_f32 v[16:17], v[32:33], v[16:17]
	v_cvt_pk_bf16_f32 v14, v14, v15
	v_pk_mul_f32 v[18:19], v[18:19], v[34:35] op_sel_hi:[1,0]
	v_cvt_pk_bf16_f32 v15, v16, v17
	global_store_dwordx2 v[2:3], v[14:15], off
	global_load_dwordx4 v[14:17], v[0:1], off offset:1024
	v_pk_mul_f32 v[20:21], v[20:21], v[34:35] op_sel_hi:[1,0]
	s_waitcnt vmcnt(0)
	v_pk_mul_f32 v[14:15], v[14:15], v[18:19]
	v_pk_mul_f32 v[16:17], v[16:17], v[20:21]
	v_cvt_pk_bf16_f32 v14, v14, v15
	v_pk_mul_f32 v[18:19], v[22:23], v[34:35] op_sel_hi:[1,0]
	v_cvt_pk_bf16_f32 v15, v16, v17
	global_store_dwordx2 v[2:3], v[14:15], off offset:512
	global_load_dwordx4 v[14:17], v[0:1], off offset:2048
	v_pk_mul_f32 v[20:21], v[24:25], v[34:35] op_sel_hi:[1,0]
	s_waitcnt vmcnt(0)
	v_pk_mul_f32 v[14:15], v[14:15], v[18:19]
	v_pk_mul_f32 v[16:17], v[16:17], v[20:21]
	v_cvt_pk_bf16_f32 v14, v14, v15
	v_pk_mul_f32 v[18:19], v[26:27], v[34:35] op_sel_hi:[1,0]
	v_cvt_pk_bf16_f32 v15, v16, v17
	global_store_dwordx2 v[2:3], v[14:15], off offset:1024
	global_load_dwordx4 v[14:17], v[0:1], off offset:3072
	v_pk_mul_f32 v[20:21], v[28:29], v[34:35] op_sel_hi:[1,0]
	s_waitcnt vmcnt(0)
	v_pk_mul_f32 v[14:15], v[18:19], v[14:15]
	v_pk_mul_f32 v[16:17], v[20:21], v[16:17]
	v_cvt_pk_bf16_f32 v14, v14, v15
	s_nop 0
	v_cvt_pk_bf16_f32 v15, v16, v17
	global_store_dwordx2 v[2:3], v[14:15], off offset:1536
	v_lshl_add_u64 v[2:3], v[2:3], 0, s[4:5]
	s_cbranch_scc0 .LBB0_284

; __device__ __forceinline__ unsigned pkbf(float lo, float hi) { return pg8::cvt_pk_bf16(lo, hi); }
; __device__ __forceinline__ void unpack8bf(const u32x4 w, float* f) { f[0] = bflo(w.x); f[1] = bfhi(w.x); f[2] = bflo(w.y); f[3] = bfhi(w.y); f[4] = bflo(w.z); f[5] = bfhi(w.z); f[6] = bflo(w.w); f[7] = bfhi(w.w); }
; __device__ __forceinline__ void norm_row_bf(const bf16_t* src, const float* gain, bf16_t* ob, float* of, int lane) {
;     float v[16]; float s = 0.f;
;     const u32x4 w0 = *((const u32x4*)src + lane), w1 = *((const u32x4*)src + lane + 64);
;     unpack8bf(w0, v); unpack8bf(w1, v + 8);
; #pragma unroll
;     for (int e = 0; e < 16; ++e) s += v[e] * v[e];
;     const float rstd = 1.0f / sqrtf(wave_sum(s) * (1.f / DM) + NORM_EPS);
; #pragma unroll
;     for (int h = 0; h < 2; ++h) { const float* g = gain + h * 512 + lane * 8; const f32x4 g0 = *(const f32x4*)g, g1 = *(const f32x4*)(g + 4);
;         float o[8];
; #pragma unroll
;         for (int e = 0; e < 4; ++e) { o[e] = v[h * 8 + e] * rstd * g0[e]; o[4 + e] = v[h * 8 + 4 + e] * rstd * g1[e]; }
;         if (ob) { u32x4 w; w.x = pkbf(o[0], o[1]); w.y = pkbf(o[2], o[3]); w.z = pkbf(o[4], o[5]); w.w = pkbf(o[6], o[7]); *((u32x4*)ob + lane + 64 * h) = w; }
;         else { const f32x4 a = {o[0], o[1], o[2], o[3]}, b = {o[4], o[5], o[6], o[7]}; *(f32x4*)(of + h * 512 + lane * 8) = a; *(f32x4*)(of + h * 512 + lane * 8 + 4) = b; } }
; }
.LBB0_1302:
	v_add_co_u32_e32 v12, vcc, 0xe9800000, v2
	s_add_i32 s6, s6, s88
	s_nop 0
	v_addc_co_u32_e32 v13, vcc, -1, v3, vcc
	global_load_dwordx4 v[12:15], v[12:13], off nt
	v_add_co_u32_e32 v28, vcc, 0xe9801000, v2
	s_cmp_gt_i32 s6, 0xbfff
	s_nop 0
	v_addc_co_u32_e32 v29, vcc, -1, v3, vcc
	global_load_dwordx4 v[16:19], v[28:29], off offset:-3072 nt
	global_load_dwordx4 v[20:23], v[0:1], off offset:16
	global_load_dwordx4 v[24:27], v[0:1], off
	s_waitcnt vmcnt(3)
	v_lshlrev_b32_e32 v28, 16, v12
	v_and_b32_e32 v12, 0xffff0000, v12
	v_lshlrev_b32_e32 v29, 16, v13
	v_and_b32_e32 v13, 0xffff0000, v13
	s_waitcnt vmcnt(2)
	v_lshlrev_b32_e32 v32, 16, v16
	v_and_b32_e32 v33, 0xffff0000, v16
	v_mul_f32_e32 v16, v12, v12
	v_fmac_f32_e32 v16, v28, v28
	v_fmac_f32_e32 v16, v29, v29
	v_lshlrev_b32_e32 v30, 16, v14
	v_fmac_f32_e32 v16, v13, v13
	v_and_b32_e32 v14, 0xffff0000, v14
	v_fmac_f32_e32 v16, v30, v30
	v_lshlrev_b32_e32 v31, 16, v15
	v_fmac_f32_e32 v16, v14, v14
	v_and_b32_e32 v15, 0xffff0000, v15
	v_fmac_f32_e32 v16, v31, v31
	v_fmac_f32_e32 v16, v15, v15
	v_fmac_f32_e32 v16, v32, v32
	v_lshlrev_b32_e32 v34, 16, v17
	v_fmac_f32_e32 v16, v33, v33
	v_and_b32_e32 v35, 0xffff0000, v17
	v_fmac_f32_e32 v16, v34, v34
	v_lshlrev_b32_e32 v36, 16, v18
	v_fmac_f32_e32 v16, v35, v35
	v_and_b32_e32 v37, 0xffff0000, v18
	v_fmac_f32_e32 v16, v36, v36
	v_lshlrev_b32_e32 v38, 16, v19
	v_fmac_f32_e32 v16, v37, v37
	v_and_b32_e32 v39, 0xffff0000, v19
	v_fmac_f32_e32 v16, v38, v38
	v_fmac_f32_e32 v16, v39, v39
	ds_bpermute_b32 v17, v4, v16
	s_waitcnt lgkmcnt(0)
	v_add_f32_e32 v16, v16, v17
	ds_bpermute_b32 v17, v5, v16
	s_waitcnt lgkmcnt(0)
	v_add_f32_e32 v16, v16, v17
	ds_bpermute_b32 v17, v6, v16
	s_waitcnt lgkmcnt(0)
	v_add_f32_e32 v16, v16, v17
	ds_bpermute_b32 v17, v7, v16
	s_waitcnt lgkmcnt(0)
	v_add_f32_e32 v16, v16, v17
	ds_bpermute_b32 v17, v8, v16
	s_waitcnt lgkmcnt(0)
	v_add_f32_e32 v16, v16, v17
	ds_bpermute_b32 v17, v9, v16
	s_waitcnt lgkmcnt(0)
	v_add_f32_e32 v16, v16, v17
	v_fmamk_f32 v16, v16, 0x3a800000, v10
	v_mul_f32_e32 v17, 0x4f800000, v16
	v_cmp_gt_f32_e32 vcc, s3, v16
	s_nop 1
	v_cndmask_b32_e32 v16, v16, v17, vcc
	v_sqrt_f32_e32 v17, v16
	s_nop 0
	v_add_u32_e32 v18, -1, v17
	v_add_u32_e32 v19, 1, v17
	v_fma_f32 v40, -v18, v17, v16
	v_fma_f32 v41, -v19, v17, v16
	v_cmp_ge_f32_e64 s[0:1], 0, v40
	s_nop 1
	v_cndmask_b32_e64 v17, v17, v18, s[0:1]
	v_cmp_lt_f32_e64 s[0:1], 0, v41
	s_nop 1
	v_cndmask_b32_e64 v17, v17, v19, s[0:1]
	v_mul_f32_e32 v18, 0x37800000, v17
	v_cndmask_b32_e32 v17, v17, v18, vcc
	v_cmp_class_f32_e32 vcc, v16, v11
	s_nop 1
	v_cndmask_b32_e32 v16, v17, v16, vcc
	v_div_scale_f32 v17, s[0:1], v16, v16, 1.0
	v_rcp_f32_e32 v18, v17
	v_div_scale_f32 v19, vcc, 1.0, v16, 1.0
	v_fma_f32 v40, -v17, v18, 1.0
	v_fmac_f32_e32 v18, v40, v18
	v_mul_f32_e32 v40, v19, v18
	v_fma_f32 v41, -v17, v40, v19
	v_fmac_f32_e32 v40, v41, v18
	v_fma_f32 v17, -v17, v40, v19
	v_div_fmas_f32 v17, v17, v18, v40
	v_div_fixup_f32 v40, v17, v16, 1.0
	v_mul_f32_e32 v12, v40, v12
	v_mul_f32_e32 v14, v40, v14
	v_mul_f32_e32 v13, v40, v13
	v_mul_f32_e32 v15, v40, v15
	v_mul_f32_e32 v16, v40, v28
	v_mul_f32_e32 v17, v40, v30
	v_mul_f32_e32 v18, v40, v29
	v_mul_f32_e32 v19, v40, v31
	s_waitcnt vmcnt(0)
	v_mul_f32_e32 v12, v25, v12
	v_mul_f32_e32 v14, v21, v14
	v_mul_f32_e32 v13, v27, v13
	v_mul_f32_e32 v15, v23, v15
	v_mul_f32_e32 v16, v24, v16
	v_mul_f32_e32 v17, v20, v17
	v_mul_f32_e32 v18, v26, v18
	v_mul_f32_e32 v19, v22, v19
	v_cvt_pk_bf16_f32 v12, v16, v12
	v_cvt_pk_bf16_f32 v13, v18, v13
	v_cvt_pk_bf16_f32 v14, v17, v14
	v_cvt_pk_bf16_f32 v15, v19, v15
	global_store_dwordx4 v[2:3], v[12:15], off
	global_load_dwordx4 v[12:15], v[0:1], off offset:2048
	s_nop 0
	global_load_dwordx4 v[16:19], v[0:1], off offset:2064
	v_mul_f32_e32 v20, v40, v32
	v_mul_f32_e32 v22, v40, v33
	v_mul_f32_e32 v24, v40, v34
	v_mul_f32_e32 v26, v40, v35
	v_mul_f32_e32 v21, v40, v36
	v_mul_f32_e32 v23, v40, v37
	v_mul_f32_e32 v25, v40, v38
	v_mul_f32_e32 v27, v40, v39
	s_waitcnt vmcnt(1)
	v_mul_f32_e32 v12, v12, v20
	v_mul_f32_e32 v13, v13, v22
	v_mul_f32_e32 v14, v14, v24
	v_mul_f32_e32 v15, v15, v26
	s_waitcnt vmcnt(0)
	v_mul_f32_e32 v16, v16, v21
	v_mul_f32_e32 v17, v17, v23
	v_mul_f32_e32 v18, v18, v25
	v_mul_f32_e32 v19, v19, v27
	v_cvt_pk_bf16_f32 v12, v12, v13
	v_cvt_pk_bf16_f32 v13, v14, v15
	v_cvt_pk_bf16_f32 v14, v16, v17
	v_cvt_pk_bf16_f32 v15, v18, v19
	global_store_dwordx4 v[2:3], v[12:15], off offset:1024
	v_lshl_add_u64 v[2:3], v[2:3], 0, s[4:5]
	s_cbranch_scc0 .LBB0_1302
